# attention-phase code shifted by 16 bytes (padding), later phases keep their placement; G2 loop rewrite + lean past-K epilogue
# speedup vs baseline: 1.0096x; 1.0013x over previous
.LBB0_870:
	s_andn2_b64 vcc, exec, s[0:1]
	s_cbranch_vccnz .LBB0_1228
	s_nop 0
	s_nop 0
	s_nop 0
	s_nop 0
	v_mov_b32_e32 v211, v0
	s_load_dwordx2 s[12:13], s[82:83], 0x100
	v_writelane_b32 v253, s82, 39
	s_load_dwordx4 s[4:7], s[82:83], 0x70
	v_readfirstlane_b32 s9, v211
	s_mov_b32 s15, s79
	s_ashr_i32 s1, s9, 6
	s_lshl_b32 s78, s60, 9
	s_lshl_b64 s[10:11], s[14:15], 2
	s_waitcnt lgkmcnt(0)
	s_add_u32 s30, s4, s10
	s_addc_u32 s31, s5, s11
	s_add_u32 s34, s6, s10
	s_addc_u32 s35, s7, s11
	s_lshl_b64 s[4:5], s[78:79], 2
	s_add_u32 s0, s12, s4
	v_and_b32_e32 v2, 63, v211
	s_addc_u32 s3, s13, s5
	v_writelane_b32 v253, s83, 40
	v_lshlrev_b32_e32 v4, 2, v2
	v_and_b32_e32 v2, 64, v210
	s_add_u32 s0, s0, 0x10000
	v_add_u32_e32 v2, 64, v2
	v_xor_b32_e32 v5, 1, v210
	v_writelane_b32 v253, s0, 41
	s_addc_u32 s0, s3, 0
	v_cmp_lt_i32_e32 vcc, v5, v2
	v_xor_b32_e32 v6, 2, v210
	v_writelane_b32 v253, s0, 42
	s_lshl_b32 s0, s60, 23
	v_cndmask_b32_e32 v5, v210, v5, vcc
	v_cmp_lt_i32_e32 vcc, v6, v2
	v_xor_b32_e32 v7, 4, v210
	v_writelane_b32 v253, s0, 43
	s_add_i32 s0, 0, 0x18000
	s_lshl_b32 s14, s1, 7
	v_cndmask_b32_e32 v6, v210, v6, vcc
	v_cmp_lt_i32_e32 vcc, v7, v2
	v_xor_b32_e32 v8, 8, v210
	s_lshl_b32 s81, s1, 5
	s_add_i32 s41, s0, s14
	v_cndmask_b32_e32 v7, v210, v7, vcc
	v_cmp_lt_i32_e32 vcc, v8, v2
	v_xor_b32_e32 v9, 16, v210
	s_cmp_lt_i32 s1, 2
	v_cndmask_b32_e32 v8, v210, v8, vcc
	v_cmp_lt_i32_e32 vcc, v9, v2
	v_xor_b32_e32 v10, 32, v210
	s_cselect_b64 s[4:5], -1, 0
	v_cndmask_b32_e32 v9, v210, v9, vcc
	v_cmp_lt_i32_e32 vcc, v10, v2
	v_writelane_b32 v253, s4, 44
	s_cmp_gt_i32 s1, 1
	v_cndmask_b32_e32 v2, v210, v10, vcc
	v_writelane_b32 v253, s5, 45
	s_cselect_b64 s[4:5], -1, 0
	global_load_dword v10, v4, s[34:35]
	global_load_dword v11, v4, s[34:35] offset:256
	global_load_dword v12, v4, s[34:35] offset:512
	global_load_dword v13, v4, s[30:31]
	global_load_dword v14, v4, s[30:31] offset:256
	v_writelane_b32 v253, s4, 46
	s_add_i32 s3, s81, 0x2000
	global_load_dword v4, v4, s[30:31] offset:512
	v_writelane_b32 v253, s5, 47
	s_add_u32 s4, s12, 0x7b9ea000
	v_writelane_b32 v253, s3, 48
	s_addc_u32 s5, s13, 0
	v_writelane_b32 v253, s4, 49
	s_add_u32 s3, s12, 0x7494a000
	v_lshlrev_b32_e32 v212, 2, v5
	v_writelane_b32 v253, s5, 50
	v_writelane_b32 v253, s3, 51
	s_addc_u32 s3, s13, 0
	v_writelane_b32 v253, s3, 52
	s_add_u32 s3, s12, 0x5dd80000
	v_writelane_b32 v253, s3, 53
	s_addc_u32 s3, s13, 0
	v_writelane_b32 v253, s3, 54
	s_add_u32 s3, s12, 0x7b04a000
	v_writelane_b32 v253, s3, 55
	s_addc_u32 s3, s13, 0
	v_writelane_b32 v253, s3, 56
	s_add_u32 s3, s12, 0x7b0ca000
	v_writelane_b32 v253, s3, 57
	s_addc_u32 s3, s13, 0
	s_lshl_b32 s88, s1, 12
	s_add_i32 s33, s88, 0
	v_writelane_b32 v253, s3, 58
	s_add_i32 s15, s33, 0xc000
	v_writelane_b32 v253, s15, 59
	s_add_i32 s15, s33, 0xc400
	v_writelane_b32 v253, s15, 60
	s_add_i32 s15, s33, 0xc800
	v_writelane_b32 v253, s15, 61
	s_add_i32 s15, s33, 0xcc00
	s_lshl_b32 s75, s1, 11
	v_writelane_b32 v253, s15, 62
	s_add_i32 s15, 0, 0x14000
	s_or_b32 s5, s75, 0x400
	s_add_i32 s16, s15, s75
	v_writelane_b32 v253, s16, 63
	s_add_i32 s16, s15, s5
	s_or_b32 s80, s88, 0x400
	v_writelane_b32 v254, s16, 0
	s_add_i32 s16, s0, s88
	s_or_b32 s7, s88, 0x800
	v_writelane_b32 v254, s16, 1
	s_add_i32 s16, s0, s80
	s_or_b32 s90, s88, 0xc00
	v_writelane_b32 v254, s16, 2
	s_add_i32 s16, s0, s7
	v_writelane_b32 v254, s16, 3
	s_add_i32 s0, s0, s90
	s_add_i32 s8, s75, 0
	s_add_i32 s3, s14, 0
	v_writelane_b32 v254, s0, 4
	s_add_i32 s0, 0, 0x20000
	s_add_i32 s6, s33, 0x400
	s_add_i32 s4, s33, 0x800
	s_add_i32 s74, s33, 0xc00
	s_add_i32 s10, s8, 0x8000
	s_add_i32 s89, s8, 0x8400
	s_add_i32 s11, s3, 0x24000
	s_add_i32 s16, s0, s75
	s_add_i32 s0, s0, s5
	v_writelane_b32 v254, s16, 5
	s_add_u32 s16, s12, 0x67d80000
	v_writelane_b32 v254, s0, 6
	s_addc_u32 s17, s13, 0
	v_writelane_b32 v254, s16, 7
	s_add_u32 s0, s12, 0x6e180000
	v_lshlrev_b32_e32 v5, 2, v6
	v_writelane_b32 v254, s17, 8
	v_writelane_b32 v254, s0, 9
	s_addc_u32 s0, s13, 0
	s_add_u32 s16, s12, 0x70c00000
	v_writelane_b32 v254, s0, 10
	s_addc_u32 s17, s13, 0
	v_writelane_b32 v254, s16, 11
	s_add_u32 s0, s12, 0x6b980000
	v_lshlrev_b32_e32 v6, 2, v7
	v_writelane_b32 v254, s17, 12
	v_writelane_b32 v254, s0, 13
	s_addc_u32 s0, s13, 0
	v_writelane_b32 v254, s0, 14
	s_add_u32 s0, s12, 0x7b14a000
	v_writelane_b32 v254, s0, 15
	s_addc_u32 s0, s13, 0
	v_writelane_b32 v254, s0, 16
	s_lshl_b32 s17, s1, 10
	v_readlane_b32 s0, v253, 19
	s_add_i32 s39, s0, s75
	s_add_i32 s0, s0, s5
	s_add_i32 s40, s17, 0
	s_ashr_i32 s16, s9, 7
	s_add_i32 s38, s8, 0x400
	v_writelane_b32 v254, s0, 17
	s_add_i32 s0, s40, 0x4000
	s_cmp_lt_u32 s9, 64
	v_writelane_b32 v254, s0, 18
	s_cselect_b64 s[18:19], -1, 0
	v_writelane_b32 v254, s18, 19
	s_cmp_gt_u32 s9, 63
	s_cselect_b64 s[26:27], -1, 0
	v_writelane_b32 v254, s19, 20
	s_add_i32 s0, s8, 0x6100
	v_writelane_b32 v254, s0, 21
	s_add_i32 s0, s8, 0x6500
	v_writelane_b32 v254, s0, 22
	v_readlane_b32 s0, v253, 20
	s_add_i32 s18, s0, s75
	s_add_i32 s0, s0, s5
	v_writelane_b32 v254, s18, 23
	s_add_u32 s18, s12, 0x70c02000
	v_writelane_b32 v254, s0, 24
	s_addc_u32 s19, s13, 0
	v_writelane_b32 v254, s18, 25
	s_add_i32 s0, s40, 0xa100
	v_lshlrev_b32_e32 v7, 2, v8
	v_writelane_b32 v254, s19, 26
	v_writelane_b32 v254, s0, 27
	s_add_i32 s0, s3, 0x22300
	v_writelane_b32 v254, s0, 28
	s_add_u32 s0, s12, 0x57980000
	v_writelane_b32 v254, s0, 29
	s_addc_u32 s0, s13, 0
	v_writelane_b32 v254, s0, 30
	s_add_u32 s0, s12, 0x70d4a000
	v_writelane_b32 v254, s0, 31
	s_addc_u32 s0, s13, 0
	v_writelane_b32 v254, s0, 32
	s_lshl_b32 s0, s16, 5
	s_and_b32 s93, s0, 32
	s_xor_b32 s0, s14, 0x80
	s_add_i32 s0, s77, s0
	v_writelane_b32 v254, s0, 33
	s_lshl_b32 s0, s16, 11
	s_add_i32 s0, s0, 0
	v_writelane_b32 v254, s16, 34
	s_add_i32 s0, s0, 0x23300
	v_writelane_b32 v254, s0, 35
	s_ashr_i32 s92, s9, 8
	s_and_b32 s3, s1, 1
	s_add_i32 s0, s77, s14
	v_writelane_b32 v254, s14, 36
	s_add_u32 s97, s12, 0xf580000
	v_writelane_b32 v254, s0, 37
	s_addc_u32 s0, s13, 0
	s_add_u32 s14, s12, 0x6500000
	v_writelane_b32 v254, s14, 38
	s_addc_u32 s14, s13, 0
	v_writelane_b32 v254, s14, 39
	s_add_u32 s14, s12, 0x56f80000
	v_writelane_b32 v254, s14, 40
	s_addc_u32 s14, s13, 0
	v_writelane_b32 v254, s14, 41
	s_add_u32 s14, s12, 0xe500000
	v_writelane_b32 v254, s14, 42
	s_addc_u32 s14, s13, 0
	v_writelane_b32 v254, s14, 43
	s_add_u32 s14, s12, 0x7b1ea000
	v_writelane_b32 v254, s14, 44
	s_addc_u32 s14, s13, 0
	v_writelane_b32 v254, s14, 45
	s_and_b32 s14, s9, 0xc0
	v_writelane_b32 v254, s14, 46
	s_and_b32 s9, s9, 0xfffff00
	v_writelane_b32 v254, s9, 47
	s_ashr_i32 s9, s75, 10
	s_and_b32 s14, s9, -8
	s_lshr_b32 s9, s9, 1
	v_writelane_b32 v254, s14, 48
	s_and_b32 s9, s9, 4
	v_writelane_b32 v254, s9, 49
	s_ashr_i32 s9, s5, 10
	s_waitcnt vmcnt(0)
	v_mul_f32_e32 v8, v13, v10
	v_mul_f32_e32 v10, v14, v11
	s_and_b32 s14, s9, -8
	s_lshr_b32 s9, s9, 1
	v_max_f32_e64 v8, |v8|, |v10|
	v_writelane_b32 v254, s14, 50
	s_and_b32 s9, s9, 4
	ds_bpermute_b32 v10, v212, v8
	v_writelane_b32 v254, s9, 51
	s_lshr_b32 s9, s75, 4
	v_writelane_b32 v254, s9, 52
	s_lshr_b32 s9, s5, 4
	v_writelane_b32 v254, s9, 53
	s_lshl_b32 s9, s3, 10
	v_writelane_b32 v254, s9, 54
	v_writelane_b32 v254, s15, 55
	s_add_i32 s9, s15, s17
	v_and_b32_e32 v11, 0x7fffffff, v4
	v_and_b32_e32 v13, 0x7fffffff, v12
	s_waitcnt lgkmcnt(0)
	v_max_f32_e32 v10, v10, v10
	v_writelane_b32 v254, s9, 56
	s_add_i32 s9, s40, 0x16000
	ds_bpermute_b32 v11, v212, v11
	v_max_f32_e32 v8, v8, v10
	ds_bpermute_b32 v10, v212, v13
	s_cmp_eq_u32 s1, 2
	v_writelane_b32 v254, s9, 57
	s_cselect_b64 s[14:15], -1, 0
	v_writelane_b32 v254, s14, 58
	s_add_i32 s9, s40, 0x16880
	s_waitcnt lgkmcnt(1)
	v_max_f32_e32 v11, v11, v11
	v_writelane_b32 v254, s15, 59
	v_writelane_b32 v254, s9, 60
	s_add_i32 s9, s40, 0x18880
	v_max_f32_e64 v4, |v4|, |v4|
	s_waitcnt lgkmcnt(0)
	v_max_f32_e32 v10, v10, v10
	v_max_f32_e64 v12, |v12|, |v12|
	v_writelane_b32 v254, s9, 61
	s_add_i32 s9, s40, 0x19100
	v_max_f32_e32 v4, v4, v11
	ds_bpermute_b32 v11, v5, v8
	v_max_f32_e32 v10, v12, v10
	v_writelane_b32 v254, s9, 62
	s_add_i32 s9, s40, 0x1b100
	ds_bpermute_b32 v13, v5, v4
	ds_bpermute_b32 v5, v5, v10
	v_writelane_b32 v254, s9, 63
	s_add_i32 s9, s40, 0x1b980
	s_waitcnt lgkmcnt(2)
	v_max_f32_e32 v11, v11, v11
	v_writelane_b32 v255, s9, 0
	s_add_i32 s9, s40, 0x1d980
	v_writelane_b32 v255, s9, 1
	s_lshl_b32 s9, s3, 12
	s_cmp_gt_i32 s1, 2
	s_cselect_b64 s[34:35], -1, 0
	s_xor_b32 s1, s92, s1
	s_lshl_b32 s14, s92, 12
	s_lshl_b32 s15, s92, 6
	v_max_f32_e32 v8, v8, v11
	s_waitcnt lgkmcnt(1)
	v_max_f32_e32 v11, v13, v13
	s_waitcnt lgkmcnt(0)
	v_max_f32_e32 v5, v5, v5
	s_bitcmp0_b32 s1, 0
	ds_bpermute_b32 v12, v6, v8
	v_max_f32_e32 v4, v4, v11
	v_max_f32_e32 v5, v10, v5
	s_cselect_b64 s[18:19], -1, 0
	ds_bpermute_b32 v11, v6, v4
	ds_bpermute_b32 v6, v6, v5
	v_writelane_b32 v255, s18, 2
	s_add_i32 s1, s15, 0
	s_add_i32 s16, s1, 0x16800
	v_writelane_b32 v255, s19, 3
	v_writelane_b32 v255, s16, 4
	s_add_i32 s1, s1, 0x19080
	v_writelane_b32 v255, s1, 5
	s_add_i32 s1, s8, 0x4000
	s_waitcnt lgkmcnt(2)
	v_max_f32_e32 v10, v12, v12
	v_writelane_b32 v255, s1, 6
	s_add_i32 s1, s8, 0x4400
	v_max_f32_e32 v8, v8, v10
	s_waitcnt lgkmcnt(1)
	v_max_f32_e32 v10, v11, v11
	s_waitcnt lgkmcnt(0)
	v_max_f32_e32 v6, v6, v6
	v_writelane_b32 v255, s1, 7
	s_add_i32 s1, s40, 0x1e200
	v_max_f32_e32 v4, v4, v10
	ds_bpermute_b32 v10, v7, v8
	v_max_f32_e32 v5, v5, v6
	v_writelane_b32 v255, s1, 8
	s_add_i32 s1, s40, 0x20200
	ds_bpermute_b32 v11, v7, v4
	ds_bpermute_b32 v6, v7, v5
	v_writelane_b32 v255, s1, 9
	s_add_i32 s1, s40, 0x20a80
	v_writelane_b32 v255, s1, 10
	s_add_i32 s1, s40, 0x22a80
	s_add_u32 s18, s12, 0x3d00000
	v_writelane_b32 v255, s1, 11
	s_addc_u32 s19, s13, 0
	s_waitcnt lgkmcnt(2)
	v_max_f32_e32 v7, v10, v10
	v_writelane_b32 v255, s18, 12
	s_lshl_b32 s1, s92, 16
	v_max_f32_e32 v7, v8, v7
	s_waitcnt lgkmcnt(1)
	v_max_f32_e32 v8, v11, v11
	s_waitcnt lgkmcnt(0)
	v_max_f32_e32 v6, v6, v6
	v_writelane_b32 v255, s19, 13
	s_add_i32 s24, s1, 0
	s_lshl_b32 s1, s3, 6
	v_lshlrev_b32_e32 v9, 2, v9
	v_max_f32_e32 v4, v4, v8
	v_max_f32_e32 v5, v5, v6
	v_writelane_b32 v255, s1, 14
	s_lshl_b32 s1, s3, 9
	ds_bpermute_b32 v10, v9, v4
	ds_bpermute_b32 v6, v9, v5
	v_writelane_b32 v255, s1, 15
	s_and_b32 s1, s92, 1
	s_cmp_lg_u32 s3, s1
	ds_bpermute_b32 v8, v9, v7
	s_cselect_b64 s[18:19], -1, 0
	v_writelane_b32 v255, s18, 16
	s_add_i32 s1, 0, 0x10000
	s_waitcnt lgkmcnt(2)
	v_max_f32_e32 v9, v10, v10
	s_waitcnt lgkmcnt(1)
	v_max_f32_e32 v6, v6, v6
	v_writelane_b32 v255, s19, 17
	s_add_i32 s16, s1, s75
	v_lshlrev_b32_e32 v2, 2, v2
	v_max_f32_e32 v4, v4, v9
	v_max_f32_e32 v5, v5, v6
	v_writelane_b32 v255, s16, 18
	s_add_i32 s1, s1, s5
	ds_bpermute_b32 v9, v2, v4
	ds_bpermute_b32 v6, v2, v5
	v_writelane_b32 v255, s1, 19
	s_waitcnt lgkmcnt(2)
	v_max_f32_e32 v8, v8, v8
	s_add_u32 s18, s12, 0x70c04000
	v_writelane_b32 v255, s12, 20
	v_max_f32_e32 v7, v7, v8
	s_addc_u32 s19, s13, 0
	v_writelane_b32 v255, s13, 21
	ds_bpermute_b32 v2, v2, v7
	v_writelane_b32 v255, s18, 22
	s_getreg_b32 s12, hwreg(HW_REG_XCC_ID, 0, 4)
	s_waitcnt lgkmcnt(2)
	v_max_f32_e32 v8, v9, v9
	v_writelane_b32 v255, s19, 23
	s_waitcnt lgkmcnt(1)
	v_max_f32_e32 v6, v6, v6
	v_writelane_b32 v255, s12, 24
	v_max_f32_e32 v4, v4, v8
	v_max_f32_e32 v5, v5, v6
	v_writelane_b32 v255, s17, 25
	v_mul_f32_e32 v4, v4, v5
	v_writelane_b32 v255, s9, 26
	s_bitset1_b32 s9, 14
	s_waitcnt lgkmcnt(0)
	v_max3_f32 v2, v7, v2, v4
	v_mov_b32_e32 v4, 0x3dcccccd
	v_writelane_b32 v255, s9, 27
	v_fmamk_f32 v213, v2, 0x41a184ea, v4
	s_mov_b32 s1, 0
	s_add_i32 s82, s75, 0xc200
	s_add_i32 s83, s75, 0xc600
	s_add_i32 s29, s17, 0x10200
	s_add_i32 s31, s75, 0x10400
	s_add_i32 s30, s75, 0x10000
	v_cmp_eq_u32_e64 s[42:43], 0, v211
	v_writelane_b32 v255, s81, 28
	s_branch .LBB0_873

.LBB0_1230:
	s_andn2_b64 vcc, exec, s[0:1]
	s_cbranch_vccnz .LBB0_1331
	s_nop 0
	s_nop 0
	s_nop 0
	s_nop 0
	s_nop 0
	s_nop 0
	s_nop 0
	s_nop 0
	s_nop 0
	s_nop 0
	s_nop 0
	s_nop 0
	v_readlane_b32 s4, v252, 7
	s_mov_b64 s[0:1], s[82:83]
	v_mov_b32_e32 v1, v0
	v_readlane_b32 s5, v252, 8
	s_load_dword s3, s[4:5], 0x0
	s_mov_b32 s5, 64
	v_readlane_b32 s4, v252, 46
	v_readlane_b32 s6, v252, 47
	s_waitcnt lgkmcnt(0)
	s_cmpk_lg_i32 s3, 0x100
	s_cselect_b64 s[12:13], -1, 0
	s_cmpk_eq_i32 s3, 0x100
	s_cbranch_scc1 .LBB0_1233
	s_abs_i32 s5, s3
	v_cvt_f32_u32_e32 v1, s5
	s_sub_i32 s7, 0, s5
	s_add_i32 s4, s3, s80
	s_ashr_i32 s6, s4, 31
	v_rcp_iflag_f32_e32 v1, v1
	s_abs_i32 s4, s4
	v_mul_f32_e32 v1, 0x4f7ffffe, v1
	v_cvt_u32_f32_e32 v1, v1
	s_nop 0
	v_readfirstlane_b32 s8, v1
	s_mul_i32 s7, s7, s8
	s_mul_hi_u32 s7, s8, s7
	s_add_i32 s8, s8, s7
	s_mul_hi_u32 s7, s4, s8
	s_mul_i32 s7, s7, s5
	s_sub_i32 s4, s4, s7
	s_sub_i32 s7, s4, s5
	s_cmp_ge_u32 s4, s5
	s_cselect_b32 s4, s7, s4
	s_sub_i32 s7, s4, s5
	s_cmp_ge_u32 s4, s5
	s_cselect_b32 s4, s7, s4
	s_xor_b32 s4, s4, s6
	s_sub_i32 s4, s4, s6
	s_sub_i32 s6, s3, s4
	s_add_i32 s7, s6, 0x13f
	s_sub_i32 s6, 0xfffffec1, s6
	s_max_i32 s6, s7, s6
	s_xor_b32 s9, s7, s3
	s_mul_hi_u32 s8, s6, s8
	s_ashr_i32 s7, s9, 31
	s_mul_i32 s9, s8, s5
	s_sub_i32 s6, s6, s9
	s_add_i32 s10, s8, 1
	s_sub_i32 s9, s6, s5
	s_cmp_ge_u32 s6, s5
	s_cselect_b32 s8, s10, s8
	s_cselect_b32 s6, s9, s6
	s_add_i32 s9, s8, 1
	s_cmp_ge_u32 s6, s5
	s_cselect_b32 s5, s9, s8
	s_xor_b32 s5, s5, s7
	s_sub_i32 s6, s5, s7
	s_mov_b32 s5, s3
